# hyconv neighbour loads de-serialised + reversed channel order; attention K/V tile loads use 32-bit offsets on scalar bases (12 fewer 64-bit VALU per tile)
# speedup vs baseline: 1.0054x; 1.0054x over previous
.LBB0_567:
	s_lshl_b32 s45, s44, 1
	v_mad_u32_u24 v126, v179, s45, v130
	v_mad_u32_u24 v127, v181, s45, v130
	global_load_dwordx4 v[114:117], v126, s[42:43]
	s_nop 0
	global_load_dwordx4 v[118:121], v127, s[42:43]
	s_nop 0
	global_load_dwordx4 v[122:125], v126, s[38:39]
	s_nop 0
	global_load_dwordx4 v[126:129], v127, s[38:39]
	ds_read_b64_tr_b16 v[208:209], v176 offset:0
	ds_read_b64_tr_b16 v[210:211], v176 offset:0x800
	ds_read_b64_tr_b16 v[222:223], v176 offset:0x1000
	ds_read_b64_tr_b16 v[224:225], v176 offset:0x1800
	ds_read_b64_tr_b16 v[226:227], v176 offset:0x2000
	ds_read_b64_tr_b16 v[228:229], v176 offset:0x2800
	ds_read_b64_tr_b16 v[230:231], v176 offset:0x3000
	ds_read_b64_tr_b16 v[232:233], v176 offset:0x3800
	s_waitcnt lgkmcnt(0)
	s_nop 0
	v_mfma_f32_32x32x16_bf16 v[50:65], v[98:101], v[208:211], v[50:65]
	ds_read_b64_tr_b16 v[208:209], v176 offset:0x200
	ds_read_b64_tr_b16 v[210:211], v176 offset:0xa00
	v_mfma_f32_32x32x16_bf16 v[50:65], v[102:105], v[222:225], v[50:65]
	ds_read_b64_tr_b16 v[222:223], v176 offset:0x1200
	ds_read_b64_tr_b16 v[224:225], v176 offset:0x1a00
	v_mfma_f32_32x32x16_bf16 v[50:65], v[106:109], v[226:229], v[50:65]
	ds_read_b64_tr_b16 v[226:227], v176 offset:0x2200
	ds_read_b64_tr_b16 v[228:229], v176 offset:0x2a00
	v_mfma_f32_32x32x16_bf16 v[50:65], v[110:113], v[230:233], v[50:65]
	ds_read_b64_tr_b16 v[230:231], v176 offset:0x3200
	ds_read_b64_tr_b16 v[232:233], v176 offset:0x3a00
	s_waitcnt lgkmcnt(0)
	v_mfma_f32_32x32x16_bf16 v[34:49], v[98:101], v[208:211], v[34:49]
	ds_read_b64_tr_b16 v[208:209], v176 offset:0x400
	ds_read_b64_tr_b16 v[210:211], v176 offset:0xc00
	v_mfma_f32_32x32x16_bf16 v[34:49], v[102:105], v[222:225], v[34:49]
	ds_read_b64_tr_b16 v[222:223], v176 offset:0x1400
	ds_read_b64_tr_b16 v[224:225], v176 offset:0x1c00
	v_mfma_f32_32x32x16_bf16 v[34:49], v[106:109], v[226:229], v[34:49]
	ds_read_b64_tr_b16 v[226:227], v176 offset:0x2400
	ds_read_b64_tr_b16 v[228:229], v176 offset:0x2c00
	v_mfma_f32_32x32x16_bf16 v[34:49], v[110:113], v[230:233], v[34:49]
	ds_read_b64_tr_b16 v[230:231], v176 offset:0x3400
	ds_read_b64_tr_b16 v[232:233], v176 offset:0x3c00
	s_waitcnt lgkmcnt(0)
	v_mfma_f32_32x32x16_bf16 v[18:33], v[98:101], v[208:211], v[18:33]
	ds_read_b64_tr_b16 v[208:209], v176 offset:0x600
	ds_read_b64_tr_b16 v[210:211], v176 offset:0xe00
	v_mfma_f32_32x32x16_bf16 v[18:33], v[102:105], v[222:225], v[18:33]
	ds_read_b64_tr_b16 v[222:223], v176 offset:0x1600
	ds_read_b64_tr_b16 v[224:225], v176 offset:0x1e00
	v_mfma_f32_32x32x16_bf16 v[18:33], v[106:109], v[226:229], v[18:33]
	ds_read_b64_tr_b16 v[226:227], v176 offset:0x2600
	ds_read_b64_tr_b16 v[228:229], v176 offset:0x2e00
	v_mfma_f32_32x32x16_bf16 v[18:33], v[110:113], v[230:233], v[18:33]
	ds_read_b64_tr_b16 v[230:231], v176 offset:0x3600
	ds_read_b64_tr_b16 v[232:233], v176 offset:0x3e00
	s_waitcnt lgkmcnt(0)
	v_mfma_f32_32x32x16_bf16 v[2:17], v[98:101], v[208:211], v[2:17]
	v_max_f32_e32 v98, v83, v83
	v_max_f32_e32 v99, v82, v82
	v_max_f32_e32 v98, v99, v98
	v_max3_f32 v98, v98, v84, v85
	v_max3_f32 v98, v98, v86, v87
	v_max3_f32 v98, v98, v88, v89
	v_max3_f32 v98, v98, v90, v91
	v_max3_f32 v98, v98, v92, v93
	v_max3_f32 v98, v98, v94, v95
	v_mfma_f32_32x32x16_bf16 v[2:17], v[102:105], v[222:225], v[2:17]
	v_max3_f32 v98, v98, v96, v97
	v_max3_f32 v98, v98, v66, v67
	v_max3_f32 v98, v98, v68, v69
	v_max3_f32 v98, v98, v70, v71
	v_max3_f32 v98, v98, v72, v73
	v_max3_f32 v98, v98, v74, v75
	v_max3_f32 v98, v98, v76, v77
	v_max3_f32 v98, v98, v78, v79
	v_mfma_f32_32x32x16_bf16 v[2:17], v[106:109], v[226:229], v[2:17]
	v_max3_f32 v98, v98, v80, v81
	v_mov_b32_e32 v99, v98
	s_nop 1
	v_permlane32_swap_b32_e32 v98, v99
	v_max_f32_e32 v99, v99, v99
	v_max_f32_e32 v98, v98, v98
	v_max_f32_e32 v98, v98, v99
	v_sub_f32_e32 v99, v98, v193
	v_cmp_ge_f32_e32 vcc, s91, v99
	v_max_f32_e32 v99, v193, v193
	v_max_f32_e32 v209, v99, v98
	v_mfma_f32_32x32x16_bf16 v[2:17], v[110:113], v[230:233], v[2:17]
	v_sub_f32_e32 v98, v193, v209
	v_mul_f32_e32 v98, 0x3e0293ee, v98
	v_exp_f32_e32 v98, v98
	s_cmp_eq_u64 vcc, exec
	s_waitcnt lgkmcnt(0)
	s_barrier
	s_cselect_b64 s[38:39], -1, 0
	s_waitcnt vmcnt(0)
	v_cndmask_b32_e64 v208, v98, 1.0, s[38:39]
	v_cmp_gt_f32_e32 vcc, 1.0, v208
	s_waitcnt vmcnt(3)
	ds_write_b128 v187, v[114:117]
	s_waitcnt vmcnt(2)
	ds_write_b128 v188, v[118:121]
	s_waitcnt vmcnt(1)
	ds_write_b128 v191, v[122:125] offset:32768
	s_waitcnt vmcnt(0)
	ds_write_b128 v192, v[126:129] offset:32768
	s_cbranch_vccz .LBB0_571
	s_and_saveexec_b64 s[42:43], s[0:1]
	ds_write_b32 v177, v208 offset:128
	s_or_b64 exec, exec, s[42:43]
	s_waitcnt lgkmcnt(0)
	v_add_u32_e32 v110, s70, v164
	ds_read_b128 v[98:101], v110 offset:224
	ds_read_b128 v[102:105], v110 offset:192
	ds_read_b128 v[106:109], v110 offset:160
	ds_read_b128 v[110:113], v110 offset:128
	s_waitcnt lgkmcnt(3)
	v_pk_mul_f32 v[62:63], v[62:63], v[98:99]
	s_waitcnt lgkmcnt(2)
	v_pk_mul_f32 v[58:59], v[58:59], v[102:103]
	s_waitcnt lgkmcnt(1)
	v_pk_mul_f32 v[54:55], v[54:55], v[106:107]
	v_pk_mul_f32 v[64:65], v[64:65], v[100:101]
	v_pk_mul_f32 v[60:61], v[60:61], v[104:105]
	v_pk_mul_f32 v[56:57], v[56:57], v[108:109]
	s_waitcnt lgkmcnt(0)
	v_pk_mul_f32 v[52:53], v[52:53], v[112:113]
	v_pk_mul_f32 v[50:51], v[50:51], v[110:111]
	v_pk_mul_f32 v[46:47], v[46:47], v[98:99]
	v_pk_mul_f32 v[42:43], v[42:43], v[102:103]
	v_pk_mul_f32 v[38:39], v[38:39], v[106:107]
	v_pk_mul_f32 v[48:49], v[48:49], v[100:101]
	v_pk_mul_f32 v[44:45], v[44:45], v[104:105]
	v_pk_mul_f32 v[40:41], v[40:41], v[108:109]
	v_pk_mul_f32 v[36:37], v[36:37], v[112:113]
	v_pk_mul_f32 v[34:35], v[34:35], v[110:111]
	v_pk_mul_f32 v[30:31], v[30:31], v[98:99]
	v_pk_mul_f32 v[26:27], v[26:27], v[102:103]
	v_pk_mul_f32 v[22:23], v[22:23], v[106:107]
	v_pk_mul_f32 v[32:33], v[32:33], v[100:101]
	v_pk_mul_f32 v[28:29], v[28:29], v[104:105]
	v_pk_mul_f32 v[24:25], v[24:25], v[108:109]
	v_pk_mul_f32 v[20:21], v[20:21], v[112:113]
	v_pk_mul_f32 v[18:19], v[18:19], v[110:111]
	v_pk_mul_f32 v[14:15], v[14:15], v[98:99]
	v_pk_mul_f32 v[10:11], v[10:11], v[102:103]
	v_pk_mul_f32 v[6:7], v[6:7], v[106:107]
	v_pk_mul_f32 v[16:17], v[16:17], v[100:101]
	v_pk_mul_f32 v[12:13], v[12:13], v[104:105]
	v_pk_mul_f32 v[8:9], v[8:9], v[108:109]
	v_pk_mul_f32 v[4:5], v[4:5], v[112:113]
	v_pk_mul_f32 v[2:3], v[2:3], v[110:111]

.LBB0_578:
	s_lshl_b32 s43, s42, 1
	v_mad_u32_u24 v86, v179, s43, v130
	v_mad_u32_u24 v87, v181, s43, v130
	global_load_dwordx4 v[74:77], v86, s[40:41]
	s_nop 0
	global_load_dwordx4 v[78:81], v87, s[40:41]
	s_nop 0
	global_load_dwordx4 v[82:85], v86, s[38:39]
	s_nop 0
	global_load_dwordx4 v[86:89], v87, s[38:39]
	ds_read_b64_tr_b16 v[222:223], v195 offset:0
	ds_read_b64_tr_b16 v[224:225], v195 offset:0x800
	ds_read_b64_tr_b16 v[226:227], v195 offset:0x1000
	ds_read_b64_tr_b16 v[228:229], v195 offset:0x1800
	ds_read_b64_tr_b16 v[230:231], v195 offset:0x2000
	ds_read_b64_tr_b16 v[232:233], v195 offset:0x2800
	ds_read_b64_tr_b16 v[234:235], v195 offset:0x3000
	ds_read_b64_tr_b16 v[236:237], v195 offset:0x3800
	s_waitcnt lgkmcnt(0)
	s_nop 0
	v_mfma_f32_32x32x16_bf16 v[50:65], v[66:69], v[222:225], v[50:65]
	ds_read_b64_tr_b16 v[222:223], v195 offset:0x200
	ds_read_b64_tr_b16 v[224:225], v195 offset:0xa00
	v_mfma_f32_32x32x16_bf16 v[50:65], v[70:73], v[226:229], v[50:65]
	ds_read_b64_tr_b16 v[226:227], v195 offset:0x1200
	ds_read_b64_tr_b16 v[228:229], v195 offset:0x1a00
	v_mfma_f32_32x32x16_bf16 v[50:65], v[90:93], v[230:233], v[50:65]
	ds_read_b64_tr_b16 v[230:231], v195 offset:0x2200
	ds_read_b64_tr_b16 v[232:233], v195 offset:0x2a00
	v_mfma_f32_32x32x16_bf16 v[50:65], v[94:97], v[234:237], v[50:65]
	ds_read_b64_tr_b16 v[234:235], v195 offset:0x3200
	ds_read_b64_tr_b16 v[236:237], v195 offset:0x3a00
	s_waitcnt lgkmcnt(0)
	v_mfma_f32_32x32x16_bf16 v[34:49], v[66:69], v[222:225], v[34:49]
	ds_read_b64_tr_b16 v[222:223], v195 offset:0x400
	ds_read_b64_tr_b16 v[224:225], v195 offset:0xc00
	v_mfma_f32_32x32x16_bf16 v[34:49], v[70:73], v[226:229], v[34:49]
	ds_read_b64_tr_b16 v[226:227], v195 offset:0x1400
	ds_read_b64_tr_b16 v[228:229], v195 offset:0x1c00
	v_mfma_f32_32x32x16_bf16 v[34:49], v[90:93], v[230:233], v[34:49]
	ds_read_b64_tr_b16 v[230:231], v195 offset:0x2400
	ds_read_b64_tr_b16 v[232:233], v195 offset:0x2c00
	v_mfma_f32_32x32x16_bf16 v[34:49], v[94:97], v[234:237], v[34:49]
	ds_read_b64_tr_b16 v[234:235], v195 offset:0x3400
	ds_read_b64_tr_b16 v[236:237], v195 offset:0x3c00
	s_waitcnt lgkmcnt(0)
	v_mfma_f32_32x32x16_bf16 v[18:33], v[66:69], v[222:225], v[18:33]
	ds_read_b64_tr_b16 v[222:223], v195 offset:0x600
	ds_read_b64_tr_b16 v[224:225], v195 offset:0xe00
	v_mfma_f32_32x32x16_bf16 v[18:33], v[70:73], v[226:229], v[18:33]
	ds_read_b64_tr_b16 v[226:227], v195 offset:0x1600
	ds_read_b64_tr_b16 v[228:229], v195 offset:0x1e00
	v_mfma_f32_32x32x16_bf16 v[18:33], v[90:93], v[230:233], v[18:33]
	ds_read_b64_tr_b16 v[230:231], v195 offset:0x2600
	ds_read_b64_tr_b16 v[232:233], v195 offset:0x2e00
	v_mfma_f32_32x32x16_bf16 v[18:33], v[94:97], v[234:237], v[18:33]
	ds_read_b64_tr_b16 v[234:235], v195 offset:0x3600
	ds_read_b64_tr_b16 v[236:237], v195 offset:0x3e00
	s_waitcnt lgkmcnt(0)
	v_mfma_f32_32x32x16_bf16 v[2:17], v[66:69], v[222:225], v[2:17]
	v_max_f32_e32 v66, v115, v115
	v_max_f32_e32 v67, v114, v114
	v_max_f32_e32 v66, v67, v66
	v_max3_f32 v66, v66, v116, v117
	v_max3_f32 v66, v66, v118, v119
	v_max3_f32 v66, v66, v120, v121
	v_max3_f32 v66, v66, v122, v123
	v_max3_f32 v66, v66, v124, v125
	v_max3_f32 v66, v66, v126, v127
	v_mfma_f32_32x32x16_bf16 v[2:17], v[70:73], v[226:229], v[2:17]
	v_max3_f32 v66, v66, v128, v129
	v_max3_f32 v66, v66, v98, v99
	v_max3_f32 v66, v66, v100, v101
	v_max3_f32 v66, v66, v102, v103
	v_max3_f32 v66, v66, v104, v105
	v_max3_f32 v66, v66, v106, v107
	v_max3_f32 v66, v66, v108, v109
	v_max3_f32 v66, v66, v110, v111
	v_mfma_f32_32x32x16_bf16 v[2:17], v[90:93], v[230:233], v[2:17]
	v_max3_f32 v66, v66, v112, v113
	v_mov_b32_e32 v67, v66
	s_nop 1
	v_permlane32_swap_b32_e32 v66, v67
	v_max_f32_e32 v67, v67, v67
	v_max_f32_e32 v66, v66, v66
	v_max_f32_e32 v66, v66, v67
	v_sub_f32_e32 v67, v66, v193
	v_cmp_ge_f32_e32 vcc, s91, v67
	v_max_f32_e32 v67, v193, v193
	v_max_f32_e32 v66, v67, v66
	v_mfma_f32_32x32x16_bf16 v[2:17], v[94:97], v[234:237], v[2:17]
	v_sub_f32_e32 v67, v193, v66
	v_mul_f32_e32 v67, 0x3e0293ee, v67
	v_exp_f32_e32 v67, v67
	s_cmp_eq_u64 vcc, exec
	s_waitcnt lgkmcnt(0)
	s_barrier
	s_cselect_b64 s[38:39], -1, 0
	s_waitcnt vmcnt(0)
	v_cndmask_b32_e64 v197, v67, 1.0, s[38:39]
	v_cmp_gt_f32_e32 vcc, 1.0, v197
	s_waitcnt vmcnt(3)
	ds_write_b128 v187, v[74:77] offset:16384
	s_waitcnt vmcnt(2)
	ds_write_b128 v188, v[78:81] offset:16384
	s_waitcnt vmcnt(1)
	ds_write_b128 v191, v[82:85] offset:49152
	s_waitcnt vmcnt(0)
	ds_write_b128 v192, v[86:89] offset:49152
	s_cbranch_vccz .LBB0_582
	s_and_saveexec_b64 s[40:41], s[0:1]
	ds_write_b32 v177, v197 offset:128
	s_or_b64 exec, exec, s[40:41]
	s_waitcnt lgkmcnt(0)
	v_add_u32_e32 v67, s70, v164
	ds_read_b128 v[68:71], v67 offset:224
	ds_read_b128 v[72:75], v67 offset:192
	ds_read_b128 v[76:79], v67 offset:128
	ds_read_b128 v[80:83], v67 offset:160
	s_waitcnt lgkmcnt(3)
	v_pk_mul_f32 v[64:65], v[64:65], v[70:71]
	v_pk_mul_f32 v[62:63], v[62:63], v[68:69]
	s_waitcnt lgkmcnt(2)
	v_pk_mul_f32 v[60:61], v[60:61], v[74:75]
	v_pk_mul_f32 v[58:59], v[58:59], v[72:73]
	s_waitcnt lgkmcnt(0)
	v_pk_mul_f32 v[56:57], v[56:57], v[82:83]
	v_pk_mul_f32 v[54:55], v[54:55], v[80:81]
	v_pk_mul_f32 v[52:53], v[52:53], v[78:79]
	v_pk_mul_f32 v[50:51], v[50:51], v[76:77]
	v_pk_mul_f32 v[48:49], v[48:49], v[70:71]
	v_pk_mul_f32 v[46:47], v[46:47], v[68:69]
	v_pk_mul_f32 v[44:45], v[44:45], v[74:75]
	v_pk_mul_f32 v[42:43], v[42:43], v[72:73]
	v_pk_mul_f32 v[40:41], v[40:41], v[82:83]
	v_pk_mul_f32 v[38:39], v[38:39], v[80:81]
	v_pk_mul_f32 v[36:37], v[36:37], v[78:79]
	v_pk_mul_f32 v[34:35], v[34:35], v[76:77]
	v_pk_mul_f32 v[32:33], v[32:33], v[70:71]
	v_pk_mul_f32 v[30:31], v[30:31], v[68:69]
	v_pk_mul_f32 v[28:29], v[28:29], v[74:75]
	v_pk_mul_f32 v[26:27], v[26:27], v[72:73]
	v_pk_mul_f32 v[24:25], v[24:25], v[82:83]
	v_pk_mul_f32 v[22:23], v[22:23], v[80:81]
	v_pk_mul_f32 v[20:21], v[20:21], v[78:79]
	v_pk_mul_f32 v[18:19], v[18:19], v[76:77]
	v_pk_mul_f32 v[16:17], v[16:17], v[70:71]
	v_pk_mul_f32 v[14:15], v[14:15], v[68:69]
	v_pk_mul_f32 v[12:13], v[12:13], v[74:75]
	v_pk_mul_f32 v[10:11], v[10:11], v[72:73]
	v_pk_mul_f32 v[8:9], v[8:9], v[82:83]
	v_pk_mul_f32 v[6:7], v[6:7], v[80:81]
	v_pk_mul_f32 v[4:5], v[4:5], v[78:79]
	v_pk_mul_f32 v[2:3], v[2:3], v[76:77]
